# conv tap-table staging de-serialized too: 10 masked loads in flight, one wait, 10 LDS writes
# baseline (speedup 1.0000x reference)
; #define LAS __attribute__((address_space(3)))
; __global__ void __launch_bounds__(512, 2) fwd_megakernel(Args args) {
;     ...
;             for (int i = tid; i < 37 * 128; i += 512) {
;                 const int rowi = i >> 7;
;                 f32x4 v = {0.f, 0.f, 0.f, 0.f};
;                 if (rowi >= 3 && rowi <= 33) v = ((const f32x4*)conv_w)[i - 3 * 128];
;                 ((LAS f32x4*)lds)[i] = v;
;             }
.LBB0_1168:
	s_movk_i32 s0, 0x1280
	v_cmp_gt_i32_e32 vcc, s0, v170
	s_waitcnt lgkmcnt(0)
	s_barrier
	s_and_saveexec_b64 s[0:1], vcc
	v_readlane_b32 s14, v252, 50
	v_readlane_b32 s15, v252, 51
	s_cbranch_execz .LBB0_1173
	v_readlane_b32 s2, v255, 28
	s_mul_hi_i32 s3, s2, 0xf800
	s_mul_i32 s2, s2, 0xf800
	v_readlane_b32 s4, v254, 50
	s_add_u32 s2, s4, s2
	v_readlane_b32 s4, v254, 51
	v_ashrrev_i32_e32 v171, 31, v170
	s_addc_u32 s3, s4, s3
	v_lshl_add_u64 v[4:5], v[170:171], 4, s[2:3]
	v_lshl_add_u32 v6, v170, 4, 0
	s_mov_b64 s[2:3], 0x2000
	v_ashrrev_i32_e32 v7, 7, v170
	v_add_u32_e32 v0, -3, v7
	v_cmp_gt_u32_e32 vcc, 31, v0
	v_mov_b32_e32 v34, 0
	v_mov_b32_e32 v35, 0
	v_mov_b32_e32 v36, 0
	v_mov_b32_e32 v37, 0
	s_and_saveexec_b64 s[4:5], vcc
	global_load_dwordx4 v[34:37], v[4:5], off
	s_or_b64 exec, exec, s[4:5]
	v_lshl_add_u64 v[4:5], v[4:5], 0, s[2:3]
	v_add_u32_e32 v0, 1, v7
	v_cmp_gt_u32_e32 vcc, 31, v0
	v_mov_b32_e32 v38, 0
	v_mov_b32_e32 v39, 0
	v_mov_b32_e32 v40, 0
	v_mov_b32_e32 v41, 0
	s_and_saveexec_b64 s[4:5], vcc
	global_load_dwordx4 v[38:41], v[4:5], off
	s_or_b64 exec, exec, s[4:5]
	v_lshl_add_u64 v[4:5], v[4:5], 0, s[2:3]
	v_add_u32_e32 v0, 5, v7
	v_cmp_gt_u32_e32 vcc, 31, v0
	v_mov_b32_e32 v42, 0
	v_mov_b32_e32 v43, 0
	v_mov_b32_e32 v44, 0
	v_mov_b32_e32 v45, 0
	s_and_saveexec_b64 s[4:5], vcc
	global_load_dwordx4 v[42:45], v[4:5], off
	s_or_b64 exec, exec, s[4:5]
	v_lshl_add_u64 v[4:5], v[4:5], 0, s[2:3]
	v_add_u32_e32 v0, 9, v7
	v_cmp_gt_u32_e32 vcc, 31, v0
	v_mov_b32_e32 v46, 0
	v_mov_b32_e32 v47, 0
	v_mov_b32_e32 v48, 0
	v_mov_b32_e32 v49, 0
	s_and_saveexec_b64 s[4:5], vcc
	global_load_dwordx4 v[46:49], v[4:5], off
	s_or_b64 exec, exec, s[4:5]
	v_lshl_add_u64 v[4:5], v[4:5], 0, s[2:3]
	v_add_u32_e32 v0, 13, v7
	v_cmp_gt_u32_e32 vcc, 31, v0
	v_mov_b32_e32 v50, 0
	v_mov_b32_e32 v51, 0
	v_mov_b32_e32 v52, 0
	v_mov_b32_e32 v53, 0
	s_and_saveexec_b64 s[4:5], vcc
	global_load_dwordx4 v[50:53], v[4:5], off
	s_or_b64 exec, exec, s[4:5]
	v_lshl_add_u64 v[4:5], v[4:5], 0, s[2:3]
	v_add_u32_e32 v0, 17, v7
	v_cmp_gt_u32_e32 vcc, 31, v0
	v_mov_b32_e32 v54, 0
	v_mov_b32_e32 v55, 0
	v_mov_b32_e32 v56, 0
	v_mov_b32_e32 v57, 0
	s_and_saveexec_b64 s[4:5], vcc
	global_load_dwordx4 v[54:57], v[4:5], off
	s_or_b64 exec, exec, s[4:5]
	v_lshl_add_u64 v[4:5], v[4:5], 0, s[2:3]
	v_add_u32_e32 v0, 21, v7
	v_cmp_gt_u32_e32 vcc, 31, v0
	v_mov_b32_e32 v58, 0
	v_mov_b32_e32 v59, 0
	v_mov_b32_e32 v60, 0
	v_mov_b32_e32 v61, 0
	s_and_saveexec_b64 s[4:5], vcc
	global_load_dwordx4 v[58:61], v[4:5], off
	s_or_b64 exec, exec, s[4:5]
	v_lshl_add_u64 v[4:5], v[4:5], 0, s[2:3]
	v_add_u32_e32 v0, 25, v7
	v_cmp_gt_u32_e32 vcc, 31, v0
	v_mov_b32_e32 v62, 0
	v_mov_b32_e32 v63, 0
	v_mov_b32_e32 v64, 0
	v_mov_b32_e32 v65, 0
	s_and_saveexec_b64 s[4:5], vcc
	global_load_dwordx4 v[62:65], v[4:5], off
	s_or_b64 exec, exec, s[4:5]
	v_lshl_add_u64 v[4:5], v[4:5], 0, s[2:3]
	v_add_u32_e32 v0, 29, v7
	v_cmp_gt_u32_e32 vcc, 31, v0
	v_mov_b32_e32 v8, 0
	v_mov_b32_e32 v9, 0
	v_mov_b32_e32 v10, 0
	v_mov_b32_e32 v11, 0
	s_and_saveexec_b64 s[4:5], vcc
	global_load_dwordx4 v[8:11], v[4:5], off
	s_or_b64 exec, exec, s[4:5]
	v_lshl_add_u64 v[4:5], v[4:5], 0, s[2:3]
	v_add_u32_e32 v0, 33, v7
	v_cmp_gt_u32_e32 vcc, 31, v0
	s_movk_i32 s6, 0x80
	v_cmp_gt_u32_e64 s[6:7], s6, v170
	v_mov_b32_e32 v12, 0
	v_mov_b32_e32 v13, 0
	v_mov_b32_e32 v14, 0
	v_mov_b32_e32 v15, 0
	s_and_b64 vcc, vcc, s[6:7]
	s_and_saveexec_b64 s[4:5], vcc
	global_load_dwordx4 v[12:15], v[4:5], off
	s_or_b64 exec, exec, s[4:5]
	v_add_u32_e32 v7, 0x10000, v6
	s_nop 0
	s_waitcnt vmcnt(0)
	ds_write_b128 v6, v[34:37]
	ds_write_b128 v6, v[38:41] offset:8192
	ds_write_b128 v6, v[42:45] offset:16384
	ds_write_b128 v6, v[46:49] offset:24576
	ds_write_b128 v6, v[50:53] offset:32768
	ds_write_b128 v6, v[54:57] offset:40960
	ds_write_b128 v6, v[58:61] offset:49152
	ds_write_b128 v6, v[62:65] offset:57344
	ds_write_b128 v7, v[8:11]
	s_movk_i32 s6, 0x80
	v_cmp_gt_u32_e64 s[6:7], s6, v170
	s_nop 1
	s_and_saveexec_b64 s[4:5], s[6:7]
	ds_write_b128 v7, v[12:15] offset:8192
	s_or_b64 exec, exec, s[4:5]
